# memory-K/V publish counter checked by the P4->P5a barrier leader; P5b entry poll and its workgroup barrier removed
# baseline (speedup 1.0000x reference)
; __device__ __forceinline__ void xcd_local_bar(unsigned* ctr, unsigned target, bool leader) {
;     asm volatile("s_waitcnt vmcnt(0) lgkmcnt(0)" ::: "memory");
;     __syncthreads();
;     if (leader) {
;         __hip_atomic_fetch_add(ctr, 1u, __ATOMIC_RELAXED, __HIP_MEMORY_SCOPE_AGENT);
;         while (__hip_atomic_load(ctr, __ATOMIC_RELAXED, __HIP_MEMORY_SCOPE_AGENT) < target) __builtin_amdgcn_s_sleep(1);
;         __builtin_amdgcn_fence(__ATOMIC_ACQUIRE, "agent");
;         asm volatile("s_waitcnt vmcnt(0)" ::: "memory");
.LBB0_586:
	s_or_b64 exec, exec, s[28:29]
	buffer_inv sc1
	v_mov_b32_e32 v0, 0
	global_load_dword v2, v0, s[18:19] offset:2560 sc1
	global_load_dword v1, v0, s[14:15] offset:256 sc1
	s_waitcnt vmcnt(0)
	v_cmp_le_u32_e32 vcc, s24, v1
	s_cbranch_vccnz .LBB0_588

; __device__ __forceinline__ void xcd_local_bar(unsigned* ctr, unsigned target, bool leader) {
;     ...
;     if (leader) {
;         __hip_atomic_fetch_add(ctr, 1u, __ATOMIC_RELAXED, __HIP_MEMORY_SCOPE_AGENT);
;         while (__hip_atomic_load(ctr, __ATOMIC_RELAXED, __HIP_MEMORY_SCOPE_AGENT) < target) __builtin_amdgcn_s_sleep(1);
;         __builtin_amdgcn_fence(__ATOMIC_ACQUIRE, "agent");
;         asm volatile("s_waitcnt vmcnt(0)" ::: "memory");
.Lrd3_poll:
	v_cmp_lt_u32_e32 vcc, 63, v2
	s_cbranch_vccnz .Lrd3_ok
	s_sleep 2
	global_load_dword v2, v0, s[18:19] offset:2560 sc1
	s_waitcnt vmcnt(0)
	s_branch .Lrd3_poll

; __device__ __forceinline__ int hw_lane() { int l = (int)__builtin_amdgcn_mbcnt_hi(~0u, __builtin_amdgcn_mbcnt_lo(~0u, 0u)); asm volatile("" : "+v"(l)); return l; }
; __device__ __forceinline__ gptr_t opq_ptr(const void* p) { gptr_t g = (gptr_t)p; asm volatile("" : "+s"(g)); return g; }
; __device__ __forceinline__ void xattn_unit(int tb, int h, const bf16* QX, const bf16* KX, const bf16* VXT, bf16* OX, int wid, int lane, LAS unsigned char* ldsl) {
;     ...
;         for (int i = 0; i < 8; ++i) { const int idx = tid + i * NTHR, key = idx >> 4, c = idx & 15; kt[i] = *(const u32x4*)(KX + ((size_t)b * 256 + key) * 512 + h * 128 + c * 8); }
; #pragma unroll
;         for (int i = 0; i < 8; ++i) { const int idx = tid + i * NTHR, d = idx >> 5, q = idx & 31; vt[i] = *(const u32x4*)(VXT + ((size_t)(b * 4 + h) * 128 + d) * 256 + q * 8); }
; __global__ void __launch_bounds__(NTHR, 2) hybrid_fwd(Args args) {
;     ...
;     if (use_xcd) { if (wave == 0 && hw_lane() == 0) { while (__hip_atomic_load((unsigned*)opq_ptr(args.ws) + 64 * 10, __ATOMIC_RELAXED, __HIP_MEMORY_SCOPE_AGENT) < (unsigned)((TM / 256) * 4)) __builtin_amdgcn_s_sleep(2);
;           __builtin_amdgcn_fence(__ATOMIC_ACQUIRE, "agent"); asm volatile("s_waitcnt vmcnt(0)" ::: "memory"); }
;       __syncthreads(); }
;     { const int lane = hw_lane(); const int upb = ((T / 256) * 4 + G - 1) / G; for (int i = 0; i < upb; ++i) { const int un = hb * upb + i; if (un >= (T / 256) * 4) break; xattn_unit(un >> 2, un & 3, QX, KX, VXT, OX, wave, lane, ldsl); } }
.LBB0_644:
	s_waitcnt lgkmcnt(0)
	s_waitcnt lgkmcnt(0)
	s_waitcnt lgkmcnt(0)
	s_waitcnt lgkmcnt(0)
	s_waitcnt lgkmcnt(0)
	s_mov_b32 s28, 6
	s_waitcnt lgkmcnt(0)
	s_ashr_i32 s29, s28, 31
	s_waitcnt lgkmcnt(0)
	s_waitcnt lgkmcnt(0)
	s_waitcnt lgkmcnt(0)
	s_waitcnt lgkmcnt(0)
	s_waitcnt lgkmcnt(0)
	s_waitcnt lgkmcnt(0)
	s_waitcnt lgkmcnt(0)
	s_waitcnt lgkmcnt(0)
	s_waitcnt lgkmcnt(0)
	s_waitcnt lgkmcnt(0)
	s_waitcnt lgkmcnt(0)
	s_waitcnt lgkmcnt(0)
	s_waitcnt lgkmcnt(0)
	s_and_b64 vcc, exec, s[8:9]
	s_waitcnt lgkmcnt(0)
	s_cbranch_vccnz .LBB0_654
.LBB0_654:
	s_add_i32 s12, s20, 0x1ff
	s_ashr_i32 s13, s12, 31
	s_abs_i32 s12, s12
	s_mul_hi_u32 s14, s12, s62
	s_mul_i32 s15, s14, s61
	s_sub_i32 s12, s12, s15
	s_xor_b32 s13, s13, s21
	s_add_i32 s15, s14, 1
	s_sub_i32 s25, s12, s61
	s_cmp_ge_u32 s12, s61
	s_cselect_b32 s14, s15, s14
	s_cselect_b32 s12, s25, s12
	s_add_i32 s15, s14, 1
	s_cmp_ge_u32 s12, s61
	s_cselect_b32 s12, s15, s14
	s_xor_b32 s12, s12, s13
	s_sub_i32 s30, s12, s13
	v_mov_b32_e32 v0, v212
	s_cmp_lt_i32 s30, 1
	s_cbranch_scc1 .LBB0_661
	v_add_u32_e32 v3, s71, v0
	v_ashrrev_i32_e32 v4, 4, v3
	v_ashrrev_i32_e32 v5, 31, v4
	v_add_u32_e32 v6, 0x200, v3
	v_lshlrev_b64 v[124:125], 10, v[4:5]
	v_ashrrev_i32_e32 v4, 4, v6
	v_ashrrev_i32_e32 v5, 31, v4
	v_add_u32_e32 v7, 0x400, v3
	v_lshlrev_b64 v[126:127], 10, v[4:5]
	v_ashrrev_i32_e32 v4, 4, v7
	v_ashrrev_i32_e32 v5, 31, v4
	v_add_u32_e32 v8, 0x600, v3
	v_lshlrev_b64 v[128:129], 10, v[4:5]
	v_ashrrev_i32_e32 v4, 4, v8
	v_ashrrev_i32_e32 v5, 31, v4
	v_add_u32_e32 v9, 0x800, v3
	v_lshlrev_b64 v[130:131], 10, v[4:5]
	v_ashrrev_i32_e32 v4, 4, v9
	v_ashrrev_i32_e32 v5, 31, v4
	v_add_u32_e32 v10, 0xa00, v3
	v_lshlrev_b64 v[132:133], 10, v[4:5]
	v_ashrrev_i32_e32 v4, 4, v10
	v_ashrrev_i32_e32 v5, 31, v4
	v_add_u32_e32 v11, 0xc00, v3
	v_lshlrev_b64 v[134:135], 10, v[4:5]
	v_ashrrev_i32_e32 v4, 4, v11
	v_ashrrev_i32_e32 v5, 31, v4
	v_add_u32_e32 v12, 0xe00, v3
	v_lshlrev_b64 v[136:137], 10, v[4:5]
	v_ashrrev_i32_e32 v4, 4, v12
	v_mov_b32_e32 v121, 0
	v_ashrrev_i32_e32 v5, 31, v4
	v_lshlrev_b32_e32 v13, 4, v0
	v_lshlrev_b64 v[138:139], 10, v[4:5]
	v_and_b32_e32 v4, 0x1f0, v13
	v_mov_b32_e32 v5, v121
	s_mul_i32 s31, s30, s24
	s_cmp_eq_u32 s20, 0x100
	s_cbranch_scc0 .Lp5b_keepmap
	s_lshr_b32 s98, s24, 4
	s_lshl_b32 s98, s98, 3
	s_and_b32 s99, s24, 7
	s_add_i32 s98, s98, s99
	s_lshl_b32 s98, s98, 2
	s_bfe_u32 s99, s24, 0x10003
	s_lshl_b32 s99, s99, 1
	s_add_i32 s31, s98, s99
